# scalar-base staging DMA also in the in-proj tail-round loop and the out-proj K-loop (no 64-bit VALU address adds in any GEMM loop)
# speedup vs baseline: 1.0046x; 1.0046x over previous
; #define PG8_STAGE(bufoff, gbase, voff) do { _Pragma("unroll") for (int _i = 0; _i < 2; ++_i) \
;         __builtin_amdgcn_global_load_lds((const unsigned*)((const char*)(gbase) + (voff)[_i]), (PG8_LAS unsigned*)(lds + (bufoff) + ldsw + _i * 8192), 16, 0, 0); } while (0)
; #define PG8_LDA(dst, b, h) do { _Pragma("unroll") for (int m = 0; m < 4; ++m) _Pragma("unroll") for (int k = 0; k < 2; ++k) dst[m][k] = *(const PG8_LAS bf16x8*)(lds + PG8_SA(b, h) + aoff + m * 2048 + k * 1024); } while (0)
; #define PG8_LDB(dst, b, h) do { _Pragma("unroll") for (int n = 0; n < 2; ++n) _Pragma("unroll") for (int k = 0; k < 2; ++k) dst[n][k] = *(const PG8_LAS bf16x8*)(lds + PG8_SB(b, h) + boff + n * 2048 + k * 1024); } while (0)
; #define PG8_MMA(ai, bj, At, Bt) do { __builtin_amdgcn_s_setprio(1); _Pragma("unroll") for (int m = 0; m < 4; ++m) _Pragma("unroll") for (int n = 0; n < 2; ++n) _Pragma("unroll") for (int k = 0; k < 2; ++k) \
;         acc[ai][bj][m][n] = __builtin_amdgcn_mfma_f32_16x16x32_bf16(Bt[n][k], At[m][k], acc[ai][bj][m][n], 0, 0, 0); __builtin_amdgcn_s_setprio(0); } while (0)
; #define PG8_WAIT_V(n) asm volatile("s_waitcnt vmcnt(" #n ")" ::: "memory")
; #define PG8_WAIT_L(n) asm volatile("s_waitcnt lgkmcnt(" #n ")" ::: "memory")
; #define PG8_BAR __builtin_amdgcn_s_barrier()
; #define PG8_SCHED __builtin_amdgcn_sched_barrier(0)
; template <class Epi, class Sched, bool ALIGN_EPI = false, bool SP2 = false>
; __device__ __forceinline__ void gemm_phase(PG8_LAS unsigned char* lds, const Gemm g, const Sched& S, const Epi& E) {
;     ...
;             PG8_LDB(B0, 0, 0); PG8_LDB(B1, 0, 1); PG8_SCHED; PG8_LDA(At, 0, 0); PG8_STAGE(PG8_SA(1, 1), a1 + hstep, voffA);
;             PG8_WAIT_V(8); PG8_WAIT_L(0); PG8_BAR; PG8_MMA(0, 0, At, B0); PG8_MMA(0, 1, At, B1); PG8_BAR; PG8_SCHED;
;             PG8_LDA(At, 0, 1); PG8_STAGE(PG8_SB(0, 0), b2, voffB); PG8_STAGE(PG8_SB(0, 1), b2 + hstep, voffB); PG8_STAGE(PG8_SA(0, 0), a2, voffA);
;             PG8_WAIT_V(8); PG8_WAIT_L(0); PG8_BAR; PG8_MMA(1, 0, At, B0); PG8_MMA(1, 1, At, B1); PG8_BAR; PG8_SCHED;
.LBB0_180:
	ds_read_b128 v[130:133], v242
	ds_read_b128 v[134:137], v242 offset:1024
	ds_read_b128 v[138:141], v242 offset:2048
	ds_read_b128 v[142:145], v242 offset:3072
	ds_read_b128 v[146:149], v243
	ds_read_b128 v[150:153], v243 offset:1024
	ds_read_b128 v[164:167], v243 offset:2048
	ds_read_b128 v[168:171], v243 offset:3072
	s_add_u32 s80, s78, 0xfff80080
	s_addc_u32 s81, s79, -1
	s_cmp_eq_u32 s52, 28
	s_cselect_b32 s83, s25, s81
	s_cselect_b32 s82, s27, s80
	s_cselect_b32 s81, s23, s51
	s_cselect_b32 s80, s37, s47
	s_add_i32 m0, s7, 0xc000
	ds_read_b128 v[172:175], v179
	ds_read_b128 v[180:183], v179 offset:1024
	ds_read_b128 v[184:187], v179 offset:2048
	ds_read_b128 v[188:191], v179 offset:3072
	ds_read_b128 v[192:195], v179 offset:4096
	ds_read_b128 v[196:199], v179 offset:5120
	ds_read_b128 v[200:203], v179 offset:6144
	ds_read_b128 v[208:211], v179 offset:7168
	global_load_lds_dwordx4 v160, s[78:79]
	s_add_i32 m0, s7, 0xe000
	s_nop 0
	global_load_lds_dwordx4 v162, s[78:79]
	s_waitcnt vmcnt(8)
	s_waitcnt lgkmcnt(0)
	s_barrier
	s_setprio 1
	v_mfma_f32_16x16x32_bf16 v[126:129], v[130:133], v[172:175], v[126:129]
	v_mfma_f32_16x16x32_bf16 v[122:125], v[138:141], v[172:175], v[122:125]
	v_mfma_f32_16x16x32_bf16 v[110:113], v[130:133], v[184:187], v[110:113]
	v_mfma_f32_16x16x32_bf16 v[106:109], v[138:141], v[184:187], v[106:109]
	v_mfma_f32_16x16x32_bf16 v[94:97], v[130:133], v[192:195], v[94:97]
	v_mfma_f32_16x16x32_bf16 v[90:93], v[138:141], v[192:195], v[90:93]
	v_mfma_f32_16x16x32_bf16 v[78:81], v[130:133], v[200:203], v[78:81]
	v_mfma_f32_16x16x32_bf16 v[74:77], v[138:141], v[200:203], v[74:77]
	v_mfma_f32_16x16x32_bf16 v[126:129], v[134:137], v[180:183], v[126:129]
	v_mfma_f32_16x16x32_bf16 v[122:125], v[142:145], v[180:183], v[122:125]
	v_mfma_f32_16x16x32_bf16 v[110:113], v[134:137], v[188:191], v[110:113]
	v_mfma_f32_16x16x32_bf16 v[106:109], v[142:145], v[188:191], v[106:109]
	v_mfma_f32_16x16x32_bf16 v[94:97], v[134:137], v[196:199], v[94:97]
	v_mfma_f32_16x16x32_bf16 v[90:93], v[142:145], v[196:199], v[90:93]
	v_mfma_f32_16x16x32_bf16 v[78:81], v[134:137], v[208:211], v[78:81]
	v_mfma_f32_16x16x32_bf16 v[74:77], v[142:145], v[208:211], v[74:77]
	v_mfma_f32_16x16x32_bf16 v[118:121], v[146:149], v[172:175], v[118:121]
	v_mfma_f32_16x16x32_bf16 v[114:117], v[164:167], v[172:175], v[114:117]
	v_mfma_f32_16x16x32_bf16 v[102:105], v[146:149], v[184:187], v[102:105]
	v_mfma_f32_16x16x32_bf16 v[98:101], v[164:167], v[184:187], v[98:101]
	v_mfma_f32_16x16x32_bf16 v[86:89], v[146:149], v[192:195], v[86:89]
	v_mfma_f32_16x16x32_bf16 v[82:85], v[164:167], v[192:195], v[82:85]
	v_mfma_f32_16x16x32_bf16 v[70:73], v[146:149], v[200:203], v[70:73]
	v_mfma_f32_16x16x32_bf16 v[66:69], v[164:167], v[200:203], v[66:69]
	v_mfma_f32_16x16x32_bf16 v[118:121], v[150:153], v[180:183], v[118:121]
	v_mfma_f32_16x16x32_bf16 v[114:117], v[168:171], v[180:183], v[114:117]
	v_mfma_f32_16x16x32_bf16 v[102:105], v[150:153], v[188:191], v[102:105]
	v_mfma_f32_16x16x32_bf16 v[98:101], v[168:171], v[188:191], v[98:101]
	v_mfma_f32_16x16x32_bf16 v[86:89], v[150:153], v[196:199], v[86:89]
	v_mfma_f32_16x16x32_bf16 v[82:85], v[168:171], v[196:199], v[82:85]
	v_mfma_f32_16x16x32_bf16 v[70:73], v[150:153], v[208:211], v[70:73]
	v_mfma_f32_16x16x32_bf16 v[66:69], v[168:171], v[208:211], v[66:69]
	s_setprio 0
	s_barrier
	s_add_i32 s84, s88, s6
	s_mov_b32 m0, s84
	ds_read_b128 v[172:175], v179 offset:16384
	ds_read_b128 v[180:183], v179 offset:17408
	ds_read_b128 v[184:187], v179 offset:18432
	ds_read_b128 v[188:191], v179 offset:19456
	ds_read_b128 v[192:195], v179 offset:20480
	ds_read_b128 v[196:199], v179 offset:21504
	ds_read_b128 v[200:203], v179 offset:22528
	ds_read_b128 v[208:211], v179 offset:23552
	global_load_lds_dwordx4 v0, s[80:81]
	s_add_i32 m0, s84, 0x2000
	s_add_u32 s84, s80, 0x80000
	s_addc_u32 s85, s81, 0
	s_add_i32 s86, s89, s6
	global_load_lds_dwordx4 v158, s[80:81]
	s_mov_b32 m0, s86
	s_nop 0
	global_load_lds_dwordx4 v0, s[84:85]
	s_add_i32 m0, s86, 0x2000
	s_nop 0
	global_load_lds_dwordx4 v158, s[84:85]
	s_mov_b32 m0, s7
	s_nop 0
	global_load_lds_dwordx4 v154, s[82:83]
	s_mov_b32 m0, s8
	s_nop 0
	global_load_lds_dwordx4 v156, s[82:83]
	s_waitcnt vmcnt(8)
	s_waitcnt lgkmcnt(0)
	s_barrier
	s_setprio 1
	v_mfma_f32_16x16x32_bf16 v[62:65], v[130:133], v[172:175], v[62:65]
	v_mfma_f32_16x16x32_bf16 v[58:61], v[138:141], v[172:175], v[58:61]
	v_mfma_f32_16x16x32_bf16 v[46:49], v[130:133], v[184:187], v[46:49]
	v_mfma_f32_16x16x32_bf16 v[42:45], v[138:141], v[184:187], v[42:45]
	v_mfma_f32_16x16x32_bf16 v[30:33], v[130:133], v[192:195], v[30:33]
	v_mfma_f32_16x16x32_bf16 v[26:29], v[138:141], v[192:195], v[26:29]
	v_mfma_f32_16x16x32_bf16 v[14:17], v[130:133], v[200:203], v[14:17]
	v_mfma_f32_16x16x32_bf16 v[10:13], v[138:141], v[200:203], v[10:13]
	v_mfma_f32_16x16x32_bf16 v[62:65], v[134:137], v[180:183], v[62:65]
	v_mfma_f32_16x16x32_bf16 v[58:61], v[142:145], v[180:183], v[58:61]
	v_mfma_f32_16x16x32_bf16 v[46:49], v[134:137], v[188:191], v[46:49]
	v_mfma_f32_16x16x32_bf16 v[42:45], v[142:145], v[188:191], v[42:45]
	v_mfma_f32_16x16x32_bf16 v[30:33], v[134:137], v[196:199], v[30:33]
	v_mfma_f32_16x16x32_bf16 v[26:29], v[142:145], v[196:199], v[26:29]
	v_mfma_f32_16x16x32_bf16 v[14:17], v[134:137], v[208:211], v[14:17]
	v_mfma_f32_16x16x32_bf16 v[10:13], v[142:145], v[208:211], v[10:13]
	v_mfma_f32_16x16x32_bf16 v[54:57], v[146:149], v[172:175], v[54:57]
	v_mfma_f32_16x16x32_bf16 v[50:53], v[164:167], v[172:175], v[50:53]
	v_mfma_f32_16x16x32_bf16 v[38:41], v[146:149], v[184:187], v[38:41]
	v_mfma_f32_16x16x32_bf16 v[34:37], v[164:167], v[184:187], v[34:37]
	v_mfma_f32_16x16x32_bf16 v[22:25], v[146:149], v[192:195], v[22:25]
	v_mfma_f32_16x16x32_bf16 v[18:21], v[164:167], v[192:195], v[18:21]
	v_mfma_f32_16x16x32_bf16 v[6:9], v[146:149], v[200:203], v[6:9]
	v_mfma_f32_16x16x32_bf16 v[2:5], v[164:167], v[200:203], v[2:5]
	v_mfma_f32_16x16x32_bf16 v[54:57], v[150:153], v[180:183], v[54:57]
	v_mfma_f32_16x16x32_bf16 v[50:53], v[168:171], v[180:183], v[50:53]
	v_mfma_f32_16x16x32_bf16 v[38:41], v[150:153], v[188:191], v[38:41]
	v_mfma_f32_16x16x32_bf16 v[34:37], v[168:171], v[188:191], v[34:37]
	v_mfma_f32_16x16x32_bf16 v[22:25], v[150:153], v[196:199], v[22:25]
	v_mfma_f32_16x16x32_bf16 v[18:21], v[168:171], v[196:199], v[18:21]
	v_mfma_f32_16x16x32_bf16 v[6:9], v[150:153], v[208:211], v[6:9]
	v_mfma_f32_16x16x32_bf16 v[2:5], v[168:171], v[208:211], v[2:5]
	s_setprio 0
	s_barrier
; #define PG8_STAGE(bufoff, gbase, voff) do { _Pragma("unroll") for (int _i = 0; _i < 2; ++_i) \
;         __builtin_amdgcn_global_load_lds((const unsigned*)((const char*)(gbase) + (voff)[_i]), (PG8_LAS unsigned*)(lds + (bufoff) + ldsw + _i * 8192), 16, 0, 0); } while (0)
; #define PG8_LDA(dst, b, h) do { _Pragma("unroll") for (int m = 0; m < 4; ++m) _Pragma("unroll") for (int k = 0; k < 2; ++k) dst[m][k] = *(const PG8_LAS bf16x8*)(lds + PG8_SA(b, h) + aoff + m * 2048 + k * 1024); } while (0)
; #define PG8_LDB(dst, b, h) do { _Pragma("unroll") for (int n = 0; n < 2; ++n) _Pragma("unroll") for (int k = 0; k < 2; ++k) dst[n][k] = *(const PG8_LAS bf16x8*)(lds + PG8_SB(b, h) + boff + n * 2048 + k * 1024); } while (0)
; #define PG8_MMA(ai, bj, At, Bt) do { __builtin_amdgcn_s_setprio(1); _Pragma("unroll") for (int m = 0; m < 4; ++m) _Pragma("unroll") for (int n = 0; n < 2; ++n) _Pragma("unroll") for (int k = 0; k < 2; ++k) \
;         acc[ai][bj][m][n] = __builtin_amdgcn_mfma_f32_16x16x32_bf16(Bt[n][k], At[m][k], acc[ai][bj][m][n], 0, 0, 0); __builtin_amdgcn_s_setprio(0); } while (0)
; #define PG8_WAIT_V(n) asm volatile("s_waitcnt vmcnt(" #n ")" ::: "memory")
; #define PG8_WAIT_L(n) asm volatile("s_waitcnt lgkmcnt(" #n ")" ::: "memory")
; #define PG8_BAR __builtin_amdgcn_s_barrier()
; #define PG8_SCHED __builtin_amdgcn_sched_barrier(0)
; template <class Epi, class Sched, bool ALIGN_EPI = false, bool SP2 = false>
; __device__ __forceinline__ void gemm_phase(PG8_LAS unsigned char* lds, const Gemm g, const Sched& S, const Epi& E) {
;     ...
;             PG8_LDB(B0, 1, 0); PG8_LDB(B1, 1, 1); PG8_SCHED; PG8_LDA(At, 1, 0); PG8_STAGE(PG8_SA(0, 1), a2 + hstep, voffA);
;             PG8_WAIT_V(8); PG8_WAIT_L(0); PG8_BAR; PG8_MMA(0, 0, At, B0); PG8_MMA(0, 1, At, B1); PG8_BAR; PG8_SCHED;
;             PG8_LDA(At, 1, 1); PG8_STAGE(PG8_SB(1, 0), b3, voffB); PG8_STAGE(PG8_SB(1, 1), b3 + hstep, voffB); PG8_STAGE(PG8_SA(1, 0), a3, voffA);
;             PG8_WAIT_V(8); PG8_WAIT_L(0); PG8_BAR; PG8_MMA(1, 0, At, B0); PG8_MMA(1, 1, At, B1); PG8_BAR; PG8_SCHED;
;     ...
;         if constexpr (ALIGN_EPI) { if (wr == 0) PG8_BAR; }
	ds_read_b128 v[130:133], v244
	ds_read_b128 v[134:137], v244 offset:1024
	ds_read_b128 v[138:141], v244 offset:2048
	ds_read_b128 v[142:145], v244 offset:3072
	ds_read_b128 v[146:149], v245
	ds_read_b128 v[150:153], v245 offset:1024
	ds_read_b128 v[164:167], v245 offset:2048
	ds_read_b128 v[168:171], v245 offset:3072
	s_add_u32 s84, s82, 0x80000
	s_addc_u32 s85, s83, 0
	s_mov_b32 m0, s9
	ds_read_b128 v[172:175], v179 offset:32768
	ds_read_b128 v[180:183], v179 offset:33792
	ds_read_b128 v[184:187], v179 offset:34816
	ds_read_b128 v[188:191], v179 offset:35840
	ds_read_b128 v[192:195], v179 offset:36864
	ds_read_b128 v[196:199], v179 offset:37888
	ds_read_b128 v[200:203], v179 offset:38912
	ds_read_b128 v[208:211], v179 offset:39936
	global_load_lds_dwordx4 v154, s[84:85]
	s_mov_b32 m0, s10
	s_nop 0
	global_load_lds_dwordx4 v156, s[84:85]
	s_waitcnt vmcnt(8)
	s_waitcnt lgkmcnt(0)
	s_barrier
	s_setprio 1
	v_mfma_f32_16x16x32_bf16 v[126:129], v[130:133], v[172:175], v[126:129]
	v_mfma_f32_16x16x32_bf16 v[122:125], v[138:141], v[172:175], v[122:125]
	v_mfma_f32_16x16x32_bf16 v[110:113], v[130:133], v[184:187], v[110:113]
	v_mfma_f32_16x16x32_bf16 v[106:109], v[138:141], v[184:187], v[106:109]
	v_mfma_f32_16x16x32_bf16 v[94:97], v[130:133], v[192:195], v[94:97]
	v_mfma_f32_16x16x32_bf16 v[90:93], v[138:141], v[192:195], v[90:93]
	v_mfma_f32_16x16x32_bf16 v[78:81], v[130:133], v[200:203], v[78:81]
	v_mfma_f32_16x16x32_bf16 v[74:77], v[138:141], v[200:203], v[74:77]
	v_mfma_f32_16x16x32_bf16 v[126:129], v[134:137], v[180:183], v[126:129]
	v_mfma_f32_16x16x32_bf16 v[122:125], v[142:145], v[180:183], v[122:125]
	v_mfma_f32_16x16x32_bf16 v[110:113], v[134:137], v[188:191], v[110:113]
	v_mfma_f32_16x16x32_bf16 v[106:109], v[142:145], v[188:191], v[106:109]
	v_mfma_f32_16x16x32_bf16 v[94:97], v[134:137], v[196:199], v[94:97]
	v_mfma_f32_16x16x32_bf16 v[90:93], v[142:145], v[196:199], v[90:93]
	v_mfma_f32_16x16x32_bf16 v[78:81], v[134:137], v[208:211], v[78:81]
	v_mfma_f32_16x16x32_bf16 v[74:77], v[142:145], v[208:211], v[74:77]
	v_mfma_f32_16x16x32_bf16 v[118:121], v[146:149], v[172:175], v[118:121]
	v_mfma_f32_16x16x32_bf16 v[114:117], v[164:167], v[172:175], v[114:117]
	v_mfma_f32_16x16x32_bf16 v[102:105], v[146:149], v[184:187], v[102:105]
	v_mfma_f32_16x16x32_bf16 v[98:101], v[164:167], v[184:187], v[98:101]
	v_mfma_f32_16x16x32_bf16 v[86:89], v[146:149], v[192:195], v[86:89]
	v_mfma_f32_16x16x32_bf16 v[82:85], v[164:167], v[192:195], v[82:85]
	v_mfma_f32_16x16x32_bf16 v[70:73], v[146:149], v[200:203], v[70:73]
	v_mfma_f32_16x16x32_bf16 v[66:69], v[164:167], v[200:203], v[66:69]
	v_mfma_f32_16x16x32_bf16 v[118:121], v[150:153], v[180:183], v[118:121]
	v_mfma_f32_16x16x32_bf16 v[114:117], v[168:171], v[180:183], v[114:117]
	v_mfma_f32_16x16x32_bf16 v[102:105], v[150:153], v[188:191], v[102:105]
	v_mfma_f32_16x16x32_bf16 v[98:101], v[168:171], v[188:191], v[98:101]
	v_mfma_f32_16x16x32_bf16 v[86:89], v[150:153], v[196:199], v[86:89]
	v_mfma_f32_16x16x32_bf16 v[82:85], v[168:171], v[196:199], v[82:85]
	v_mfma_f32_16x16x32_bf16 v[70:73], v[150:153], v[208:211], v[70:73]
	v_mfma_f32_16x16x32_bf16 v[66:69], v[168:171], v[208:211], v[66:69]
	s_setprio 0
	s_barrier
	s_add_i32 vcc_lo, s90, s6
	s_add_u32 s84, s80, 0x80
	s_addc_u32 s85, s81, 0
	s_mov_b32 m0, vcc_lo
	ds_read_b128 v[172:175], v179 offset:49152
	ds_read_b128 v[180:183], v179 offset:50176
	ds_read_b128 v[184:187], v179 offset:51200
	ds_read_b128 v[188:191], v179 offset:52224
	ds_read_b128 v[192:195], v179 offset:53248
	ds_read_b128 v[196:199], v179 offset:54272
	ds_read_b128 v[200:203], v179 offset:55296
	ds_read_b128 v[208:211], v179 offset:56320
	global_load_lds_dwordx4 v0, s[84:85]
	s_add_i32 m0, vcc_lo, 0x2000
	s_add_i32 vcc_lo, s6, 0x1c000
	global_load_lds_dwordx4 v158, s[84:85]
	s_add_u32 s80, s80, 0x80080
	s_addc_u32 s81, s81, 0
	s_mov_b32 m0, vcc_lo
	s_nop 0
	global_load_lds_dwordx4 v0, s[80:81]
	s_add_i32 m0, vcc_lo, 0x2000
	s_nop 0
	global_load_lds_dwordx4 v158, s[80:81]
	s_add_u32 s84, s82, 0x80
	s_addc_u32 s85, s83, 0
	s_mov_b32 m0, s12
	s_nop 0
	global_load_lds_dwordx4 v154, s[84:85]
	s_mov_b32 m0, s13
	s_nop 0
	global_load_lds_dwordx4 v156, s[84:85]
	s_waitcnt vmcnt(8)
	s_waitcnt lgkmcnt(0)
	s_barrier
	s_setprio 1
	v_mfma_f32_16x16x32_bf16 v[62:65], v[130:133], v[172:175], v[62:65]
	v_mfma_f32_16x16x32_bf16 v[58:61], v[138:141], v[172:175], v[58:61]
	v_mfma_f32_16x16x32_bf16 v[46:49], v[130:133], v[184:187], v[46:49]
	v_mfma_f32_16x16x32_bf16 v[42:45], v[138:141], v[184:187], v[42:45]
	v_mfma_f32_16x16x32_bf16 v[30:33], v[130:133], v[192:195], v[30:33]
	v_mfma_f32_16x16x32_bf16 v[26:29], v[138:141], v[192:195], v[26:29]
	v_mfma_f32_16x16x32_bf16 v[14:17], v[130:133], v[200:203], v[14:17]
	v_mfma_f32_16x16x32_bf16 v[10:13], v[138:141], v[200:203], v[10:13]
	v_mfma_f32_16x16x32_bf16 v[62:65], v[134:137], v[180:183], v[62:65]
	v_mfma_f32_16x16x32_bf16 v[58:61], v[142:145], v[180:183], v[58:61]
	v_mfma_f32_16x16x32_bf16 v[46:49], v[134:137], v[188:191], v[46:49]
	v_mfma_f32_16x16x32_bf16 v[42:45], v[142:145], v[188:191], v[42:45]
	v_mfma_f32_16x16x32_bf16 v[30:33], v[134:137], v[196:199], v[30:33]
	v_mfma_f32_16x16x32_bf16 v[26:29], v[142:145], v[196:199], v[26:29]
	v_mfma_f32_16x16x32_bf16 v[14:17], v[134:137], v[208:211], v[14:17]
	v_mfma_f32_16x16x32_bf16 v[10:13], v[142:145], v[208:211], v[10:13]
	v_mfma_f32_16x16x32_bf16 v[54:57], v[146:149], v[172:175], v[54:57]
	v_mfma_f32_16x16x32_bf16 v[50:53], v[164:167], v[172:175], v[50:53]
	v_mfma_f32_16x16x32_bf16 v[38:41], v[146:149], v[184:187], v[38:41]
	v_mfma_f32_16x16x32_bf16 v[34:37], v[164:167], v[184:187], v[34:37]
	v_mfma_f32_16x16x32_bf16 v[22:25], v[146:149], v[192:195], v[22:25]
	v_mfma_f32_16x16x32_bf16 v[18:21], v[164:167], v[192:195], v[18:21]
	v_mfma_f32_16x16x32_bf16 v[6:9], v[146:149], v[200:203], v[6:9]
	v_mfma_f32_16x16x32_bf16 v[2:5], v[164:167], v[200:203], v[2:5]
	v_mfma_f32_16x16x32_bf16 v[54:57], v[150:153], v[180:183], v[54:57]
	v_mfma_f32_16x16x32_bf16 v[50:53], v[168:171], v[180:183], v[50:53]
	v_mfma_f32_16x16x32_bf16 v[38:41], v[150:153], v[188:191], v[38:41]
	v_mfma_f32_16x16x32_bf16 v[34:37], v[168:171], v[188:191], v[34:37]
	v_mfma_f32_16x16x32_bf16 v[22:25], v[150:153], v[196:199], v[22:25]
	v_mfma_f32_16x16x32_bf16 v[18:21], v[168:171], v[196:199], v[18:21]
	v_mfma_f32_16x16x32_bf16 v[6:9], v[150:153], v[208:211], v[6:9]
	v_mfma_f32_16x16x32_bf16 v[2:5], v[168:171], v[208:211], v[2:5]
	s_setprio 0
	s_add_i32 s52, s52, 2
	s_add_u32 s78, s78, 0x100
	s_addc_u32 s79, s79, 0
	s_add_u32 s47, s47, 0x100
	s_addc_u32 s51, s51, 0
	s_cmp_gt_u32 s52, 29
	s_barrier
	s_cbranch_scc0 .LBB0_180
	s_and_b64 vcc, exec, s[18:19]
	s_cbranch_vccz .LBB0_183
	s_barrier

; #define PG8_STAGE(bufoff, gbase, voff) do { _Pragma("unroll") for (int _i = 0; _i < 2; ++_i) \
;         __builtin_amdgcn_global_load_lds((const unsigned*)((const char*)(gbase) + (voff)[_i]), (PG8_LAS unsigned*)(lds + (bufoff) + ldsw + _i * 8192), 16, 0, 0); } while (0)
; #define PG8_LDA(dst, b, h) do { _Pragma("unroll") for (int m = 0; m < 4; ++m) _Pragma("unroll") for (int k = 0; k < 2; ++k) dst[m][k] = *(const PG8_LAS bf16x8*)(lds + PG8_SA(b, h) + aoff + m * 2048 + k * 1024); } while (0)
; #define PG8_LDB(dst, b, h) do { _Pragma("unroll") for (int n = 0; n < 2; ++n) _Pragma("unroll") for (int k = 0; k < 2; ++k) dst[n][k] = *(const PG8_LAS bf16x8*)(lds + PG8_SB(b, h) + boff + n * 2048 + k * 1024); } while (0)
; #define PG8_MMA(ai, bj, At, Bt) do { __builtin_amdgcn_s_setprio(1); _Pragma("unroll") for (int m = 0; m < 4; ++m) _Pragma("unroll") for (int n = 0; n < 2; ++n) _Pragma("unroll") for (int k = 0; k < 2; ++k) \
;         acc[ai][bj][m][n] = __builtin_amdgcn_mfma_f32_16x16x32_bf16(Bt[n][k], At[m][k], acc[ai][bj][m][n], 0, 0, 0); __builtin_amdgcn_s_setprio(0); } while (0)
; #define PG8_WAIT_V(n) asm volatile("s_waitcnt vmcnt(" #n ")" ::: "memory")
; #define PG8_WAIT_L(n) asm volatile("s_waitcnt lgkmcnt(" #n ")" ::: "memory")
; #define PG8_BAR __builtin_amdgcn_s_barrier()
; #define PG8_SCHED __builtin_amdgcn_sched_barrier(0)
; template <class Epi, class Sched, bool ALIGN_EPI = false, bool SP2 = false>
; __device__ __forceinline__ void gemm_phase(PG8_LAS unsigned char* lds, const Gemm g, const Sched& S, const Epi& E) {
;     ...
;             PG8_LDB(B0, 0, 0); PG8_LDB(B1, 0, 1); PG8_SCHED; PG8_LDA(At, 0, 0); PG8_STAGE(PG8_SA(1, 1), a1 + hstep, voffA);
;             PG8_WAIT_V(8); PG8_WAIT_L(0); PG8_BAR; PG8_MMA(0, 0, At, B0); PG8_MMA(0, 1, At, B1); PG8_BAR; PG8_SCHED;
;             PG8_LDA(At, 0, 1); PG8_STAGE(PG8_SB(0, 0), b2, voffB); PG8_STAGE(PG8_SB(0, 1), b2 + hstep, voffB); PG8_STAGE(PG8_SA(0, 0), a2, voffA);
;             PG8_WAIT_V(8); PG8_WAIT_L(0); PG8_BAR; PG8_MMA(1, 0, At, B0); PG8_MMA(1, 1, At, B1); PG8_BAR; PG8_SCHED;
.Ltail_loop:
	ds_read_b128 v[114:117], v242
	ds_read_b128 v[118:121], v242 offset:1024
	ds_read_b128 v[130:133], v242 offset:2048
	ds_read_b128 v[134:137], v242 offset:3072
	s_add_u32 s40, s34, 0xfff80080
	s_addc_u32 s41, s35, -1
	s_cmp_eq_u32 s46, 28
	s_cselect_b32 s43, s15, s41
	s_cselect_b32 s42, s19, s40
	s_cselect_b32 s41, s17, s45
	s_cselect_b32 s40, s37, s44
	s_add_i32 m0, s8, 0xc000
	ds_read_b128 v[180:183], v178
	ds_read_b128 v[184:187], v178 offset:1024
	ds_read_b128 v[188:191], v178 offset:2048
	ds_read_b128 v[192:195], v178 offset:3072
	ds_read_b128 v[196:199], v178 offset:4096
	ds_read_b128 v[200:203], v178 offset:5120
	ds_read_b128 v[208:211], v178 offset:6144
	ds_read_b128 v[230:233], v178 offset:7168
	global_load_lds_dwordx4 v164, s[34:35]
	s_add_i32 m0, s8, 0xe000
	s_nop 0
	global_load_lds_dwordx4 v166, s[34:35]
	s_waitcnt vmcnt(8)
	s_waitcnt lgkmcnt(0)
	s_barrier
	s_setprio 1
	v_mfma_f32_16x16x32_bf16 v[142:145], v[114:117], v[180:183], v[142:145]
	v_mfma_f32_16x16x32_bf16 v[138:141], v[130:133], v[180:183], v[138:141]
	v_mfma_f32_16x16x32_bf16 v[110:113], v[114:117], v[188:191], v[110:113]
	v_mfma_f32_16x16x32_bf16 v[106:109], v[130:133], v[188:191], v[106:109]
	v_mfma_f32_16x16x32_bf16 v[94:97], v[114:117], v[196:199], v[94:97]
	v_mfma_f32_16x16x32_bf16 v[90:93], v[130:133], v[196:199], v[90:93]
	v_mfma_f32_16x16x32_bf16 v[78:81], v[114:117], v[208:211], v[78:81]
	v_mfma_f32_16x16x32_bf16 v[74:77], v[130:133], v[208:211], v[74:77]
	v_mfma_f32_16x16x32_bf16 v[142:145], v[118:121], v[184:187], v[142:145]
	v_mfma_f32_16x16x32_bf16 v[138:141], v[134:137], v[184:187], v[138:141]
	v_mfma_f32_16x16x32_bf16 v[110:113], v[118:121], v[192:195], v[110:113]
	v_mfma_f32_16x16x32_bf16 v[106:109], v[134:137], v[192:195], v[106:109]
	v_mfma_f32_16x16x32_bf16 v[94:97], v[118:121], v[200:203], v[94:97]
	v_mfma_f32_16x16x32_bf16 v[90:93], v[134:137], v[200:203], v[90:93]
	v_mfma_f32_16x16x32_bf16 v[78:81], v[118:121], v[230:233], v[78:81]
	v_mfma_f32_16x16x32_bf16 v[74:77], v[134:137], v[230:233], v[74:77]
	s_setprio 0
	s_barrier
	s_add_i32 s47, s88, s6
	s_mov_b32 m0, s47
	ds_read_b128 v[180:183], v178 offset:16384
	ds_read_b128 v[184:187], v178 offset:17408
	ds_read_b128 v[188:191], v178 offset:18432
	ds_read_b128 v[192:195], v178 offset:19456
	ds_read_b128 v[196:199], v178 offset:20480
	ds_read_b128 v[200:203], v178 offset:21504
	ds_read_b128 v[208:211], v178 offset:22528
	ds_read_b128 v[230:233], v178 offset:23552
	global_load_lds_dwordx4 v0, s[40:41]
	s_add_i32 m0, s47, 0x2000
	s_add_u32 s50, s40, 0x80000
	s_addc_u32 s51, s41, 0
	s_add_i32 s47, s89, s6
	global_load_lds_dwordx4 v154, s[40:41]
	s_mov_b32 m0, s47
	s_nop 0
	global_load_lds_dwordx4 v0, s[50:51]
	s_add_i32 m0, s47, 0x2000
	s_nop 0
	global_load_lds_dwordx4 v154, s[50:51]
	s_mov_b32 m0, s8
	s_nop 0
	global_load_lds_dwordx4 v158, s[42:43]
	s_mov_b32 m0, s9
	s_nop 0
	global_load_lds_dwordx4 v156, s[42:43]
	s_waitcnt vmcnt(8)
	s_waitcnt lgkmcnt(0)
	s_barrier
	s_setprio 1
	v_mfma_f32_16x16x32_bf16 v[62:65], v[114:117], v[180:183], v[62:65]
	v_mfma_f32_16x16x32_bf16 v[58:61], v[130:133], v[180:183], v[58:61]
	v_mfma_f32_16x16x32_bf16 v[46:49], v[114:117], v[188:191], v[46:49]
	v_mfma_f32_16x16x32_bf16 v[42:45], v[130:133], v[188:191], v[42:45]
	v_mfma_f32_16x16x32_bf16 v[30:33], v[114:117], v[196:199], v[30:33]
	v_mfma_f32_16x16x32_bf16 v[26:29], v[130:133], v[196:199], v[26:29]
	v_mfma_f32_16x16x32_bf16 v[14:17], v[114:117], v[208:211], v[14:17]
	v_mfma_f32_16x16x32_bf16 v[10:13], v[130:133], v[208:211], v[10:13]
	v_mfma_f32_16x16x32_bf16 v[62:65], v[118:121], v[184:187], v[62:65]
	v_mfma_f32_16x16x32_bf16 v[58:61], v[134:137], v[184:187], v[58:61]
	v_mfma_f32_16x16x32_bf16 v[46:49], v[118:121], v[192:195], v[46:49]
	v_mfma_f32_16x16x32_bf16 v[42:45], v[134:137], v[192:195], v[42:45]
	v_mfma_f32_16x16x32_bf16 v[30:33], v[118:121], v[200:203], v[30:33]
	v_mfma_f32_16x16x32_bf16 v[26:29], v[134:137], v[200:203], v[26:29]
	v_mfma_f32_16x16x32_bf16 v[14:17], v[118:121], v[230:233], v[14:17]
	v_mfma_f32_16x16x32_bf16 v[10:13], v[134:137], v[230:233], v[10:13]
	s_setprio 0
	s_barrier
; #define PG8_STAGE(bufoff, gbase, voff) do { _Pragma("unroll") for (int _i = 0; _i < 2; ++_i) \
;         __builtin_amdgcn_global_load_lds((const unsigned*)((const char*)(gbase) + (voff)[_i]), (PG8_LAS unsigned*)(lds + (bufoff) + ldsw + _i * 8192), 16, 0, 0); } while (0)
; #define PG8_LDA(dst, b, h) do { _Pragma("unroll") for (int m = 0; m < 4; ++m) _Pragma("unroll") for (int k = 0; k < 2; ++k) dst[m][k] = *(const PG8_LAS bf16x8*)(lds + PG8_SA(b, h) + aoff + m * 2048 + k * 1024); } while (0)
; #define PG8_LDB(dst, b, h) do { _Pragma("unroll") for (int n = 0; n < 2; ++n) _Pragma("unroll") for (int k = 0; k < 2; ++k) dst[n][k] = *(const PG8_LAS bf16x8*)(lds + PG8_SB(b, h) + boff + n * 2048 + k * 1024); } while (0)
; #define PG8_MMA(ai, bj, At, Bt) do { __builtin_amdgcn_s_setprio(1); _Pragma("unroll") for (int m = 0; m < 4; ++m) _Pragma("unroll") for (int n = 0; n < 2; ++n) _Pragma("unroll") for (int k = 0; k < 2; ++k) \
;         acc[ai][bj][m][n] = __builtin_amdgcn_mfma_f32_16x16x32_bf16(Bt[n][k], At[m][k], acc[ai][bj][m][n], 0, 0, 0); __builtin_amdgcn_s_setprio(0); } while (0)
; #define PG8_WAIT_V(n) asm volatile("s_waitcnt vmcnt(" #n ")" ::: "memory")
; #define PG8_WAIT_L(n) asm volatile("s_waitcnt lgkmcnt(" #n ")" ::: "memory")
; #define PG8_BAR __builtin_amdgcn_s_barrier()
; #define PG8_SCHED __builtin_amdgcn_sched_barrier(0)
; template <class Epi, class Sched, bool ALIGN_EPI = false, bool SP2 = false>
; __device__ __forceinline__ void gemm_phase(PG8_LAS unsigned char* lds, const Gemm g, const Sched& S, const Epi& E) {
;     ...
;         for (int t = 0; t < nt; t += 2) {
;     ...
;             PG8_LDB(B0, 1, 0); PG8_LDB(B1, 1, 1); PG8_SCHED; PG8_LDA(At, 1, 0); PG8_STAGE(PG8_SA(0, 1), a2 + hstep, voffA);
;             PG8_WAIT_V(8); PG8_WAIT_L(0); PG8_BAR; PG8_MMA(0, 0, At, B0); PG8_MMA(0, 1, At, B1); PG8_BAR; PG8_SCHED;
;             PG8_LDA(At, 1, 1); PG8_STAGE(PG8_SB(1, 0), b3, voffB); PG8_STAGE(PG8_SB(1, 1), b3 + hstep, voffB); PG8_STAGE(PG8_SA(1, 0), a3, voffA);
;             PG8_WAIT_V(8); PG8_WAIT_L(0); PG8_BAR; PG8_MMA(1, 0, At, B0); PG8_MMA(1, 1, At, B1); PG8_BAR; PG8_SCHED;
	s_add_i32 s47, 0, 0x1c000
	ds_read_b128 v[114:117], v244
	ds_read_b128 v[118:121], v244 offset:1024
	ds_read_b128 v[130:133], v244 offset:2048
	ds_read_b128 v[134:137], v244 offset:3072
	s_add_u32 s50, s42, 0x80000
	s_addc_u32 s51, s43, 0
	s_mov_b32 m0, s10
	ds_read_b128 v[180:183], v178 offset:32768
	ds_read_b128 v[184:187], v178 offset:33792
	ds_read_b128 v[188:191], v178 offset:34816
	ds_read_b128 v[192:195], v178 offset:35840
	ds_read_b128 v[196:199], v178 offset:36864
	ds_read_b128 v[200:203], v178 offset:37888
	ds_read_b128 v[208:211], v178 offset:38912
	ds_read_b128 v[230:233], v178 offset:39936
	global_load_lds_dwordx4 v158, s[50:51]
	s_mov_b32 m0, s11
	s_nop 0
	global_load_lds_dwordx4 v156, s[50:51]
	s_waitcnt vmcnt(8)
	s_waitcnt lgkmcnt(0)
	s_barrier
	s_setprio 1
	v_mfma_f32_16x16x32_bf16 v[142:145], v[114:117], v[180:183], v[142:145]
	v_mfma_f32_16x16x32_bf16 v[138:141], v[130:133], v[180:183], v[138:141]
	v_mfma_f32_16x16x32_bf16 v[110:113], v[114:117], v[188:191], v[110:113]
	v_mfma_f32_16x16x32_bf16 v[106:109], v[130:133], v[188:191], v[106:109]
	v_mfma_f32_16x16x32_bf16 v[94:97], v[114:117], v[196:199], v[94:97]
	v_mfma_f32_16x16x32_bf16 v[90:93], v[130:133], v[196:199], v[90:93]
	v_mfma_f32_16x16x32_bf16 v[78:81], v[114:117], v[208:211], v[78:81]
	v_mfma_f32_16x16x32_bf16 v[74:77], v[130:133], v[208:211], v[74:77]
	v_mfma_f32_16x16x32_bf16 v[142:145], v[118:121], v[184:187], v[142:145]
	v_mfma_f32_16x16x32_bf16 v[138:141], v[134:137], v[184:187], v[138:141]
	v_mfma_f32_16x16x32_bf16 v[110:113], v[118:121], v[192:195], v[110:113]
	v_mfma_f32_16x16x32_bf16 v[106:109], v[134:137], v[192:195], v[106:109]
	v_mfma_f32_16x16x32_bf16 v[94:97], v[118:121], v[200:203], v[94:97]
	v_mfma_f32_16x16x32_bf16 v[90:93], v[134:137], v[200:203], v[90:93]
	v_mfma_f32_16x16x32_bf16 v[78:81], v[118:121], v[230:233], v[78:81]
	v_mfma_f32_16x16x32_bf16 v[74:77], v[134:137], v[230:233], v[74:77]
	s_setprio 0
	s_barrier
	s_add_i32 vcc_lo, s90, s6
	s_add_u32 s50, s40, 0x80
	s_addc_u32 s51, s41, 0
	s_mov_b32 m0, vcc_lo
	ds_read_b128 v[180:183], v178 offset:49152
	ds_read_b128 v[184:187], v178 offset:50176
	ds_read_b128 v[188:191], v178 offset:51200
	ds_read_b128 v[192:195], v178 offset:52224
	ds_read_b128 v[196:199], v178 offset:53248
	ds_read_b128 v[200:203], v178 offset:54272
	ds_read_b128 v[208:211], v178 offset:55296
	ds_read_b128 v[230:233], v178 offset:56320
	global_load_lds_dwordx4 v0, s[50:51]
	s_add_i32 m0, vcc_lo, 0x2000
	s_add_i32 vcc_lo, s47, s6
	global_load_lds_dwordx4 v154, s[50:51]
	s_add_u32 s40, s40, 0x80080
	s_addc_u32 s41, s41, 0
	s_mov_b32 m0, vcc_lo
	s_nop 0
	global_load_lds_dwordx4 v0, s[40:41]
	s_add_i32 m0, vcc_lo, 0x2000
	s_nop 0
	global_load_lds_dwordx4 v154, s[40:41]
	s_add_u32 s50, s42, 0x80
	s_addc_u32 s51, s43, 0
	s_mov_b32 m0, s13
	s_nop 0
	global_load_lds_dwordx4 v158, s[50:51]
	s_mov_b32 m0, s25
	s_nop 0
	global_load_lds_dwordx4 v156, s[50:51]
	s_waitcnt vmcnt(8)
	s_waitcnt lgkmcnt(0)
	s_barrier
	s_setprio 1
	v_mfma_f32_16x16x32_bf16 v[62:65], v[114:117], v[180:183], v[62:65]
	v_mfma_f32_16x16x32_bf16 v[58:61], v[130:133], v[180:183], v[58:61]
	v_mfma_f32_16x16x32_bf16 v[46:49], v[114:117], v[188:191], v[46:49]
	v_mfma_f32_16x16x32_bf16 v[42:45], v[130:133], v[188:191], v[42:45]
	v_mfma_f32_16x16x32_bf16 v[30:33], v[114:117], v[196:199], v[30:33]
	v_mfma_f32_16x16x32_bf16 v[26:29], v[130:133], v[196:199], v[26:29]
	v_mfma_f32_16x16x32_bf16 v[14:17], v[114:117], v[208:211], v[14:17]
	v_mfma_f32_16x16x32_bf16 v[10:13], v[130:133], v[208:211], v[10:13]
	v_mfma_f32_16x16x32_bf16 v[62:65], v[118:121], v[184:187], v[62:65]
	v_mfma_f32_16x16x32_bf16 v[58:61], v[134:137], v[184:187], v[58:61]
	v_mfma_f32_16x16x32_bf16 v[46:49], v[118:121], v[192:195], v[46:49]
	v_mfma_f32_16x16x32_bf16 v[42:45], v[134:137], v[192:195], v[42:45]
	v_mfma_f32_16x16x32_bf16 v[30:33], v[118:121], v[200:203], v[30:33]
	v_mfma_f32_16x16x32_bf16 v[26:29], v[134:137], v[200:203], v[26:29]
	v_mfma_f32_16x16x32_bf16 v[14:17], v[118:121], v[230:233], v[14:17]
	v_mfma_f32_16x16x32_bf16 v[10:13], v[134:137], v[230:233], v[10:13]
	s_setprio 0
	s_add_i32 s46, s46, 2
	s_add_u32 s34, s34, 0x100
	s_addc_u32 s35, s35, 0
	s_add_u32 s44, s44, 0x100
	s_addc_u32 s45, s45, 0
	s_cmp_gt_u32 s46, 29
	s_barrier
	s_cbranch_scc0 .Ltail_loop
	s_branch .Ltail_join
